# plus: l1rows wave-reductions batched 6-wide; static prio raise in sample-MLA item; P11 dequeue atomic issued before the barrier
# speedup vs baseline: 1.0256x; 1.0066x over previous
; DEVI int next_item(unsigned* ctr, int* slot) {
;     __syncthreads();
;     if (threadIdx.x == 0) *slot = (int)atomicAdd(ctr, 1u);
;     __syncthreads();
;     return *slot;
; }
; __global__ void __launch_bounds__(512) mega(Params p, int ph_lo, int ph_hi, int coop) {
;     ...
;         case 11: {
;             for (;;) {
;                 int it = next_item(ctr + 1 + 2 * rep, s_item_p);
;                 if (it >= 32 + 2048 + 2176) break;
.LBB0_106:
	s_and_saveexec_b64 s[0:1], s[82:83]
	s_cbranch_execz .Ldq11_a
	v_mov_b32_e32 v2, 1
	global_atomic_add v2, v1, v2, s[96:97] offset:4 sc0
.Ldq11_a:
	s_or_b64 exec, exec, s[0:1]
	s_barrier
	s_and_saveexec_b64 s[0:1], s[82:83]
	s_cbranch_execz .LBB0_110
	s_waitcnt vmcnt(0)
	ds_write_b32 v175, v2

; template <int MODE>
; DEVI void attn_item(const Params& p, int item, unsigned char* smem) {
;     ...
;     } else {
;         wactive = true;
;         for (int id = tid; id < 128 * 36; id += 512) {
;             const int rr = id / 36, ch = id % 36, hh = rr >> 4, t = rr & 15;
;             u32x4 w = ch < 32 ? *(const u32x4*)(QLAT + (size_t)(b * 16 + t) * 2048 + hh * 256 + ch * 8)
;                               : *(const u32x4*)(QF + (size_t)(NP + b * 16 + t) * 768 + hh * 96 + 64 + (ch - 32) * 8);
;             *(u32x4*)(Qs + rr * 592 + ch * 16) = w;
;         }
.LBB0_270:
	s_waitcnt vmcnt(0)
	v_readfirstlane_b32 s0, v180
	s_cmp_lt_u32 s0, 0x100
	s_cbranch_scc1 .Lprio_m2
	s_setprio 1
.Lprio_m2:
	v_mov_b32_e32 v130, v180
	s_movk_i32 s0, 0x1200
	s_nop 0
	v_cmp_gt_i32_e32 vcc, s0, v130
	s_and_saveexec_b64 s[0:1], vcc
	s_cbranch_execz .LBB0_277
	s_lshl_b32 s3, s72, 4
	v_mov_b32_e32 v2, 0xa000
	s_add_i32 s8, s3, 0x10000
	v_lshlrev_b32_e32 v0, 3, v130
	v_lshl_add_u32 v3, v130, 4, v2
	s_mov_b64 s[38:39], 0
	v_mov_b32_e32 v2, v130
	s_branch .LBB0_273

; template <int MODE>
; DEVI void attn_item(const Params& p, int item, unsigned char* smem) {
;     ...
;         const int hh = tid >> 6, v = tid & 63;
;         const float* wuv = p.in[23] + (size_t)hh * 256 * 64 + v;
;         float acc[16];
; #pragma unroll
;         for (int t = 0; t < 16; ++t) acc[t] = 0.f;
;         for (int c = 0; c < 256; ++c) {
;             const float w = wuv[(size_t)c * 64];
; #pragma unroll
;             for (int t = 0; t < 16; ++t) acc[t] += OL[(hh * 16 + t) * 256 + c] * w;
;         }
;         bf16_t* MX = (bf16_t*)(p.ws + WS_R1 + R1_MIXED2);
; #pragma unroll
;         for (int t = 0; t < 16; ++t) MX[(size_t)(NP + b * 16 + t) * 1024 + 512 + hh * 64 + v] = f2bf(acc[t]);
.LBB0_330:
	global_load_dword v72, v[66:67], off offset:-512
	v_add_u32_e32 v62, s0, v70
	ds_read_b128 v[2:5], v62
	ds_read_b128 v[6:9], v62 offset:1024
	s_add_i32 s0, s0, 16
	s_mov_b64 s[8:9], 0x400
	s_cmpk_lg_i32 s0, 0x400
	s_waitcnt lgkmcnt(1)
	v_mov_b32_e32 v13, v2
	s_waitcnt lgkmcnt(0)
	v_mov_b32_e32 v12, v6
	v_mov_b32_e32 v2, v7
	s_waitcnt vmcnt(0)
	v_pk_fma_f32 v[74:75], v[72:73], v[12:13], v[10:11] op_sel_hi:[0,1,1]
	ds_read_b128 v[10:13], v62 offset:2048
	ds_read_b128 v[14:17], v62 offset:3072
	s_waitcnt lgkmcnt(1)
	v_mov_b32_e32 v21, v10
	s_waitcnt lgkmcnt(0)
	v_mov_b32_e32 v20, v14
	v_pk_fma_f32 v[76:77], v[72:73], v[20:21], v[18:19] op_sel_hi:[0,1,1]
	ds_read_b128 v[18:21], v62 offset:4096
	ds_read_b128 v[22:25], v62 offset:5120
	v_mov_b32_e32 v10, v15
	s_waitcnt lgkmcnt(1)
	v_mov_b32_e32 v29, v18
	s_waitcnt lgkmcnt(0)
	v_mov_b32_e32 v28, v22
	v_pk_fma_f32 v[78:79], v[72:73], v[28:29], v[26:27] op_sel_hi:[0,1,1]
	ds_read_b128 v[26:29], v62 offset:6144
	ds_read_b128 v[30:33], v62 offset:7168
	v_mov_b32_e32 v18, v23
	s_waitcnt lgkmcnt(1)
	v_mov_b32_e32 v37, v26
	s_waitcnt lgkmcnt(0)
	v_mov_b32_e32 v36, v30
	v_pk_fma_f32 v[80:81], v[72:73], v[36:37], v[34:35] op_sel_hi:[0,1,1]
	ds_read_b128 v[34:37], v62 offset:8192
	ds_read_b128 v[38:41], v62 offset:9216
	v_mov_b32_e32 v26, v31
	s_waitcnt lgkmcnt(1)
	v_mov_b32_e32 v45, v34
	s_waitcnt lgkmcnt(0)
	v_mov_b32_e32 v44, v38
	v_pk_fma_f32 v[82:83], v[72:73], v[44:45], v[42:43] op_sel_hi:[0,1,1]
	ds_read_b128 v[42:45], v62 offset:10240
	ds_read_b128 v[46:49], v62 offset:11264
	v_mov_b32_e32 v34, v39
	v_mov_b32_e32 v38, v8
	v_mov_b32_e32 v39, v4
	s_waitcnt lgkmcnt(1)
	v_mov_b32_e32 v53, v42
	s_waitcnt lgkmcnt(0)
	v_mov_b32_e32 v52, v46
	v_pk_fma_f32 v[84:85], v[72:73], v[52:53], v[50:51] op_sel_hi:[0,1,1]
	ds_read_b128 v[50:53], v62 offset:12288
	ds_read_b128 v[54:57], v62 offset:13312
	v_mov_b32_e32 v42, v47
	v_mov_b32_e32 v4, v9
	s_waitcnt lgkmcnt(1)
	v_mov_b32_e32 v61, v50
	s_waitcnt lgkmcnt(0)
	v_mov_b32_e32 v60, v54
	v_pk_fma_f32 v[86:87], v[72:73], v[60:61], v[58:59] op_sel_hi:[0,1,1]
	ds_read_b128 v[58:61], v62 offset:14336
	ds_read_b128 v[62:65], v62 offset:15360
	global_load_dword v6, v[66:67], off offset:-256
	global_load_dword v8, v[66:67], off offset:256
	v_mov_b32_e32 v50, v55
	s_waitcnt lgkmcnt(1)
	v_mov_b32_e32 v89, v58
	s_waitcnt lgkmcnt(0)
	v_mov_b32_e32 v88, v62
	v_pk_fma_f32 v[68:69], v[72:73], v[88:89], v[68:69] op_sel_hi:[0,1,1]
	v_mov_b32_e32 v58, v63
	s_waitcnt vmcnt(1)
	v_pk_fma_f32 v[22:23], v[6:7], v[34:35], v[82:83] op_sel_hi:[0,1,1]
	global_load_dword v34, v[66:67], off
	v_pk_fma_f32 v[2:3], v[6:7], v[2:3], v[74:75] op_sel_hi:[0,1,1]
	v_pk_fma_f32 v[10:11], v[6:7], v[10:11], v[76:77] op_sel_hi:[0,1,1]
	v_pk_fma_f32 v[14:15], v[6:7], v[18:19], v[78:79] op_sel_hi:[0,1,1]
	v_pk_fma_f32 v[18:19], v[6:7], v[26:27], v[80:81] op_sel_hi:[0,1,1]
	v_pk_fma_f32 v[26:27], v[6:7], v[42:43], v[84:85] op_sel_hi:[0,1,1]
	v_pk_fma_f32 v[30:31], v[6:7], v[50:51], v[86:87] op_sel_hi:[0,1,1]
	v_pk_fma_f32 v[6:7], v[6:7], v[58:59], v[68:69] op_sel_hi:[0,1,1]
	v_lshl_add_u64 v[66:67], v[66:67], 0, s[8:9]
	s_waitcnt vmcnt(0)
	v_pk_fma_f32 v[2:3], v[34:35], v[38:39], v[2:3] op_sel_hi:[0,1,1]
	v_mov_b32_e32 v38, v16
	v_mov_b32_e32 v39, v12
	v_pk_fma_f32 v[38:39], v[34:35], v[38:39], v[10:11] op_sel_hi:[0,1,1]
	v_mov_b32_e32 v10, v24
	v_mov_b32_e32 v11, v20
	v_pk_fma_f32 v[14:15], v[34:35], v[10:11], v[14:15] op_sel_hi:[0,1,1]
	v_mov_b32_e32 v10, v32
	v_mov_b32_e32 v11, v28
	v_pk_fma_f32 v[42:43], v[34:35], v[10:11], v[18:19] op_sel_hi:[0,1,1]
	v_mov_b32_e32 v10, v40
	v_mov_b32_e32 v11, v36
	v_pk_fma_f32 v[22:23], v[34:35], v[10:11], v[22:23] op_sel_hi:[0,1,1]
	v_mov_b32_e32 v10, v48
	v_mov_b32_e32 v11, v44
	v_pk_fma_f32 v[46:47], v[34:35], v[10:11], v[26:27] op_sel_hi:[0,1,1]
	v_mov_b32_e32 v10, v56
	v_mov_b32_e32 v11, v52
	v_pk_fma_f32 v[30:31], v[34:35], v[10:11], v[30:31] op_sel_hi:[0,1,1]
	v_mov_b32_e32 v10, v64
	v_mov_b32_e32 v11, v60
	v_pk_fma_f32 v[6:7], v[34:35], v[10:11], v[6:7] op_sel_hi:[0,1,1]
	v_mov_b32_e32 v12, v17
	v_mov_b32_e32 v20, v25
	v_mov_b32_e32 v28, v33
	v_mov_b32_e32 v36, v41
	v_mov_b32_e32 v44, v49
	v_mov_b32_e32 v52, v57
	v_mov_b32_e32 v60, v65
	v_pk_fma_f32 v[10:11], v[8:9], v[4:5], v[2:3] op_sel_hi:[0,1,1]
	v_pk_fma_f32 v[18:19], v[8:9], v[12:13], v[38:39] op_sel_hi:[0,1,1]
	v_pk_fma_f32 v[26:27], v[8:9], v[20:21], v[14:15] op_sel_hi:[0,1,1]
	v_pk_fma_f32 v[34:35], v[8:9], v[28:29], v[42:43] op_sel_hi:[0,1,1]
	v_pk_fma_f32 v[42:43], v[8:9], v[36:37], v[22:23] op_sel_hi:[0,1,1]
	v_pk_fma_f32 v[50:51], v[8:9], v[44:45], v[46:47] op_sel_hi:[0,1,1]
	v_pk_fma_f32 v[58:59], v[8:9], v[52:53], v[30:31] op_sel_hi:[0,1,1]
	v_pk_fma_f32 v[68:69], v[8:9], v[60:61], v[6:7] op_sel_hi:[0,1,1]
	s_cbranch_scc1 .LBB0_330
	v_and_b32_e32 v2, 0xffffffc0, v130
	v_readlane_b32 s8, v252, 14
	s_lshl_b32 s0, s72, 4
	v_ashrrev_i32_e32 v3, 31, v2
	v_readlane_b32 s9, v252, 15
	v_lshlrev_b32_e32 v0, 1, v0
	s_ashr_i32 s1, s0, 31
	v_lshl_add_u64 v[2:3], v[2:3], 1, s[8:9]
	v_lshl_add_u64 v[2:3], v[2:3], 0, v[0:1]
	v_cvt_pk_bf16_f32 v0, v11, s0
	s_lshl_b64 s[0:1], s[0:1], 11
	v_lshl_add_u64 v[2:3], v[2:3], 0, s[0:1]
	v_add_co_u32_e32 v4, vcc, 0x8000000, v2
	s_nop 1
	v_addc_co_u32_e32 v5, vcc, 0, v3, vcc
	global_store_short v[4:5], v0, off
	v_cvt_pk_bf16_f32 v0, v10, s0
	global_store_short v[4:5], v0, off offset:2048
	v_add_co_u32_e32 v4, vcc, 0x8001000, v2
	v_cvt_pk_bf16_f32 v0, v19, s0
	s_nop 0
	v_addc_co_u32_e32 v5, vcc, 0, v3, vcc
	global_store_short v[4:5], v0, off
	v_cvt_pk_bf16_f32 v0, v18, s0
	global_store_short v[4:5], v0, off offset:2048
	v_add_co_u32_e32 v4, vcc, 0x8002000, v2
	v_cvt_pk_bf16_f32 v0, v27, s0
	s_nop 0
	v_addc_co_u32_e32 v5, vcc, 0, v3, vcc
	global_store_short v[4:5], v0, off
	v_cvt_pk_bf16_f32 v0, v26, s0
	global_store_short v[4:5], v0, off offset:2048
	v_add_co_u32_e32 v4, vcc, 0x8003000, v2
	v_cvt_pk_bf16_f32 v0, v35, s0
	s_nop 0
	v_addc_co_u32_e32 v5, vcc, 0, v3, vcc
	global_store_short v[4:5], v0, off
	v_cvt_pk_bf16_f32 v0, v34, s0
	global_store_short v[4:5], v0, off offset:2048
	v_add_co_u32_e32 v4, vcc, 0x8004000, v2
	v_cvt_pk_bf16_f32 v0, v43, s0
	s_nop 0
	v_addc_co_u32_e32 v5, vcc, 0, v3, vcc
	global_store_short v[4:5], v0, off
	v_cvt_pk_bf16_f32 v0, v42, s0
	global_store_short v[4:5], v0, off offset:2048
	v_add_co_u32_e32 v4, vcc, 0x8005000, v2
	v_cvt_pk_bf16_f32 v0, v51, s0
	s_nop 0
	v_addc_co_u32_e32 v5, vcc, 0, v3, vcc
	global_store_short v[4:5], v0, off
	v_cvt_pk_bf16_f32 v0, v50, s0
	global_store_short v[4:5], v0, off offset:2048
	v_add_co_u32_e32 v4, vcc, 0x8006000, v2
	v_cvt_pk_bf16_f32 v0, v59, s0
	s_nop 0
	v_addc_co_u32_e32 v5, vcc, 0, v3, vcc
	global_store_short v[4:5], v0, off
	v_cvt_pk_bf16_f32 v0, v58, s0
	v_add_co_u32_e32 v2, vcc, 0x8007000, v2
	global_store_short v[4:5], v0, off offset:2048
	v_cvt_pk_bf16_f32 v0, v69, s0
	v_addc_co_u32_e32 v3, vcc, 0, v3, vcc
	global_store_short v[2:3], v0, off
	v_cvt_pk_bf16_f32 v0, v68, s0
	global_store_short v[2:3], v0, off offset:2048
	s_setprio 0
	s_branch .LBB0_104

; DEVI void phase_l1rows(const Params& p) {
;     ...
;         float sv[2], sq[2], sk[2];
; #pragma unroll
;         for (int rr = 0; rr < 2; ++rr) {
;             sv[rr] = 0.f; sq[rr] = 0.f; sk[rr] = 0.f;
; #pragma unroll
;             for (int k = 0; k < 8; ++k) { sv[rr] += v[rr][k]; sq[rr] += cq[rr][k] * cq[rr][k]; sk[rr] += kv[rr][k] * kv[rr][k]; }
;         }
; #pragma unroll
;         for (int of = 32; of > 0; of >>= 1)
; #pragma unroll
;             for (int rr = 0; rr < 2; ++rr) { sv[rr] += __shfl_xor(sv[rr], of); sq[rr] += __shfl_xor(sq[rr], of); sk[rr] += __shfl_xor(sk[rr], of); }
.LBB0_421:
	s_or_b64 exec, exec, s[0:1]
	s_waitcnt vmcnt(0)
	v_lshlrev_b32_e32 v100, 16, v18
	v_and_b32_e32 v101, 0xffff0000, v18
	v_lshlrev_b32_e32 v102, 16, v19
	v_and_b32_e32 v103, 0xffff0000, v19
	v_lshlrev_b32_e32 v18, 16, v10
	v_and_b32_e32 v19, 0xffff0000, v10
	v_lshlrev_b32_e32 v94, 16, v6
	v_and_b32_e32 v95, 0xffff0000, v6
	v_lshlrev_b32_e32 v6, 16, v2
	v_lshlrev_b32_e32 v108, 16, v20
	v_and_b32_e32 v109, 0xffff0000, v20
	v_lshlrev_b32_e32 v110, 16, v21
	v_and_b32_e32 v111, 0xffff0000, v21
	v_lshlrev_b32_e32 v20, 16, v11
	v_and_b32_e32 v21, 0xffff0000, v11
	v_lshlrev_b32_e32 v98, 16, v7
	v_and_b32_e32 v99, 0xffff0000, v7
	v_and_b32_e32 v7, 0xffff0000, v2
	v_add_f32_e32 v33, 0, v6
	v_pk_mul_f32 v[104:105], v[94:95], v[94:95]
	v_pk_mul_f32 v[106:107], v[18:19], v[18:19]
	v_lshlrev_b32_e32 v2, 16, v3
	v_add_f32_e32 v33, v33, v7
	v_pk_mul_f32 v[122:123], v[20:21], v[20:21]
	v_add_f32_e32 v71, v104, v105
	v_add_f32_e32 v104, v106, v107
	v_lshlrev_b32_e32 v10, 16, v12
	v_and_b32_e32 v11, 0xffff0000, v12
	v_and_b32_e32 v3, 0xffff0000, v3
	v_add_f32_e32 v33, v33, v2
	v_add_f32_e32 v104, v122, v104
	v_lshlrev_b32_e32 v92, 16, v8
	v_and_b32_e32 v93, 0xffff0000, v8
	v_lshlrev_b32_e32 v8, 16, v4
	v_add_f32_e32 v33, v33, v3
	v_pk_mul_f32 v[126:127], v[10:11], v[10:11]
	v_add_f32_e32 v104, v123, v104
	v_lshlrev_b32_e32 v12, 16, v13
	v_and_b32_e32 v13, 0xffff0000, v13
	v_lshlrev_b32_e32 v96, 16, v9
	v_and_b32_e32 v97, 0xffff0000, v9
	v_and_b32_e32 v9, 0xffff0000, v4
	v_add_f32_e32 v33, v33, v8
	v_add_f32_e32 v104, v126, v104
	v_lshlrev_b32_e32 v4, 16, v5
	v_add_f32_e32 v33, v33, v9
	v_pk_mul_f32 v[130:131], v[12:13], v[12:13]
	v_add_f32_e32 v104, v127, v104
	v_lshlrev_b32_e32 v80, 16, v22
	v_and_b32_e32 v81, 0xffff0000, v22
	v_lshlrev_b32_e32 v88, 16, v14
	v_and_b32_e32 v89, 0xffff0000, v14
	v_and_b32_e32 v5, 0xffff0000, v5
	v_pk_mul_f32 v[120:121], v[98:99], v[98:99]
	v_add_f32_e32 v33, v33, v4
	v_add_f32_e32 v104, v130, v104
	v_add_f32_e32 v33, v33, v5
	v_add_f32_e32 v71, v120, v71
	v_add_f32_e32 v119, v131, v104
	v_pk_mul_f32 v[104:105], v[88:89], v[88:89]
	v_pk_mul_f32 v[106:107], v[80:81], v[80:81]
	v_pk_mul_f32 v[124:125], v[92:93], v[92:93]
	v_add_f32_e32 v71, v121, v71
	v_add_f32_e32 v104, v104, v105
	v_add_f32_e32 v105, v106, v107
	ds_bpermute_b32 v106, v112, v33
	v_add_f32_e32 v71, v124, v71
	v_pk_mul_f32 v[128:129], v[96:97], v[96:97]
	v_add_f32_e32 v71, v125, v71
	v_add_f32_e32 v71, v128, v71
	v_add_f32_e32 v71, v129, v71
	s_waitcnt lgkmcnt(0)
	v_add_f32_e32 v33, v33, v106
	ds_bpermute_b32 v106, v112, v71
	v_add_f32_e32 v120, 0, v100
	v_lshlrev_b32_e32 v90, 16, v15
	v_and_b32_e32 v91, 0xffff0000, v15
	v_add_f32_e32 v120, v120, v101
	v_add_f32_e32 v124, v120, v102
	v_pk_mul_f32 v[120:121], v[90:91], v[90:91]
	v_lshlrev_b32_e32 v14, 16, v16
	v_and_b32_e32 v15, 0xffff0000, v16
	v_add_f32_e32 v124, v124, v103
	v_add_f32_e32 v104, v120, v104
	v_add_f32_e32 v128, v124, v108
	v_pk_mul_f32 v[124:125], v[14:15], v[14:15]
	v_add_f32_e32 v104, v121, v104
	s_waitcnt lgkmcnt(0)
	v_add_f32_e32 v71, v71, v106
	ds_bpermute_b32 v106, v112, v119
	v_lshlrev_b32_e32 v16, 16, v17
	v_and_b32_e32 v17, 0xffff0000, v17
	v_add_f32_e32 v128, v128, v109
	v_add_f32_e32 v104, v124, v104
	v_lshlrev_b32_e32 v82, 16, v23
	v_and_b32_e32 v83, 0xffff0000, v23
	v_add_f32_e32 v132, v128, v110
	v_pk_mul_f32 v[128:129], v[16:17], v[16:17]
	v_add_f32_e32 v104, v125, v104
	v_pk_mul_f32 v[122:123], v[82:83], v[82:83]
	v_add_f32_e32 v104, v128, v104
	v_lshlrev_b32_e32 v22, 16, v24
	v_and_b32_e32 v23, 0xffff0000, v24
	v_add_f32_e32 v104, v129, v104
	v_add_f32_e32 v105, v122, v105
	v_pk_mul_f32 v[126:127], v[22:23], v[22:23]
	v_add_f32_e32 v105, v123, v105
	s_waitcnt lgkmcnt(0)
	v_add_f32_e32 v106, v119, v106
	ds_bpermute_b32 v119, v112, v104
	v_lshlrev_b32_e32 v24, 16, v25
	v_and_b32_e32 v25, 0xffff0000, v25
	v_add_f32_e32 v105, v126, v105
	v_pk_mul_f32 v[130:131], v[24:25], v[24:25]
	v_add_f32_e32 v105, v127, v105
	v_add_f32_e32 v105, v130, v105
	v_add_f32_e32 v105, v131, v105
	s_waitcnt lgkmcnt(0)
	v_add_f32_e32 v104, v104, v119
	ds_bpermute_b32 v119, v112, v105
	v_add_f32_e32 v132, v132, v111
	ds_bpermute_b32 v107, v112, v132
	s_waitcnt lgkmcnt(1)
	v_add_f32_e32 v105, v105, v119
	s_waitcnt lgkmcnt(0)
	v_add_f32_e32 v107, v132, v107
	ds_bpermute_b32 v144, v113, v33
	ds_bpermute_b32 v145, v113, v71
	ds_bpermute_b32 v146, v113, v106
	ds_bpermute_b32 v147, v113, v107
	ds_bpermute_b32 v148, v113, v104
	ds_bpermute_b32 v149, v113, v105
	s_waitcnt lgkmcnt(5)
	v_add_f32_e32 v33, v33, v144
	s_waitcnt lgkmcnt(4)
	v_add_f32_e32 v71, v71, v145
	s_waitcnt lgkmcnt(3)
	v_add_f32_e32 v106, v106, v146
	s_waitcnt lgkmcnt(2)
	v_add_f32_e32 v107, v107, v147
	s_waitcnt lgkmcnt(1)
	v_add_f32_e32 v104, v104, v148
	s_waitcnt lgkmcnt(0)
	v_add_f32_e32 v105, v105, v149
	ds_bpermute_b32 v144, v114, v33
	ds_bpermute_b32 v145, v114, v71
	ds_bpermute_b32 v146, v114, v106
	ds_bpermute_b32 v147, v114, v107
	ds_bpermute_b32 v148, v114, v104
	ds_bpermute_b32 v149, v114, v105
	s_waitcnt lgkmcnt(5)
	v_add_f32_e32 v33, v33, v144
	s_waitcnt lgkmcnt(4)
	v_add_f32_e32 v71, v71, v145
	s_waitcnt lgkmcnt(3)
	v_add_f32_e32 v106, v106, v146
	s_waitcnt lgkmcnt(2)
	v_add_f32_e32 v107, v107, v147
	s_waitcnt lgkmcnt(1)
; DEVI u32x4 pack8(const float* f) { u32x4 w; w.x = pk2(f[0], f[1]); w.y = pk2(f[2], f[3]); w.z = pk2(f[4], f[5]); w.w = pk2(f[6], f[7]); return w; }
; DEVI void phase_l1rows(const Params& p) {
;     ...
; #pragma unroll
;         for (int of = 32; of > 0; of >>= 1)
; #pragma unroll
;             for (int rr = 0; rr < 2; ++rr) { sv[rr] += __shfl_xor(sv[rr], of); sq[rr] += __shfl_xor(sq[rr], of); sk[rr] += __shfl_xor(sk[rr], of); }
;         float var[2];
; #pragma unroll
;         for (int rr = 0; rr < 2; ++rr) {
;             const float mu = sv[rr] * (1.f / 512.f); var[rr] = 0.f;
; #pragma unroll
;             for (int k = 0; k < 8; ++k) { v[rr][k] -= mu; var[rr] += v[rr][k] * v[rr][k]; }
;         }
; #pragma unroll
;         for (int of = 32; of > 0; of >>= 1) { var[0] += __shfl_xor(var[0], of); var[1] += __shfl_xor(var[1], of); }
; #pragma unroll
;         for (int rr = 0; rr < 2; ++rr) {
;             const int row = rowb + rr;
;             bf16_t* r = IN1 + (size_t)row * 1792;
;             {
;                 const float rs = rsqrtf(var[rr] * (1.f / 512.f) + EPS);
; #pragma unroll
;                 for (int k = 0; k < 8; ++k) v[rr][k] = v[rr][k] * rs * glng[k] + glnb[k];
;                 *(u32x4*)(r + 512 + lane * 8) = pack8(v[rr]);
;                 if (row >= NP) {
;                     float* o = p.out + O_SGUV_S + (size_t)(row - NP) * 512 + lane * 8;
;                     *(f32x4*)o = (f32x4){v[rr][0], v[rr][1], v[rr][2], v[rr][3]}; *(f32x4*)(o + 4) = (f32x4){v[rr][4], v[rr][5], v[rr][6], v[rr][7]};
;                 }
	v_add_f32_e32 v104, v104, v148
	s_waitcnt lgkmcnt(0)
	v_add_f32_e32 v105, v105, v149
	ds_bpermute_b32 v144, v115, v33
	ds_bpermute_b32 v145, v115, v71
	ds_bpermute_b32 v146, v115, v106
	ds_bpermute_b32 v147, v115, v107
	ds_bpermute_b32 v148, v115, v104
	ds_bpermute_b32 v149, v115, v105
	s_waitcnt lgkmcnt(5)
	v_add_f32_e32 v33, v33, v144
	s_waitcnt lgkmcnt(4)
	v_add_f32_e32 v71, v71, v145
	s_waitcnt lgkmcnt(3)
	v_add_f32_e32 v106, v106, v146
	s_waitcnt lgkmcnt(2)
	v_add_f32_e32 v107, v107, v147
	s_waitcnt lgkmcnt(1)
	v_add_f32_e32 v104, v104, v148
	s_waitcnt lgkmcnt(0)
	v_add_f32_e32 v105, v105, v149
	ds_bpermute_b32 v119, v116, v33
	s_waitcnt lgkmcnt(0)
	v_add_f32_e32 v121, v33, v119
	ds_bpermute_b32 v33, v116, v71
	s_waitcnt lgkmcnt(0)
	v_add_f32_e32 v71, v71, v33
	ds_bpermute_b32 v33, v116, v106
	ds_bpermute_b32 v124, v117, v71
	s_waitcnt lgkmcnt(1)
	v_add_f32_e32 v33, v106, v33
	ds_bpermute_b32 v106, v116, v107
	ds_bpermute_b32 v123, v117, v33
	s_waitcnt lgkmcnt(1)
	v_add_f32_e32 v106, v107, v106
	ds_bpermute_b32 v107, v116, v104
	s_waitcnt lgkmcnt(0)
	v_add_f32_e32 v120, v104, v107
	ds_bpermute_b32 v104, v116, v105
	ds_bpermute_b32 v122, v117, v120
	s_waitcnt lgkmcnt(1)
	v_add_f32_e32 v119, v105, v104
	ds_bpermute_b32 v105, v117, v106
	ds_bpermute_b32 v104, v117, v121
	s_waitcnt lgkmcnt(1)
	v_add_f32_e32 v105, v106, v105
	s_waitcnt lgkmcnt(0)
	v_add_f32_e32 v104, v121, v104
	v_mul_f32_e32 v128, 0x3b000000, v105
	v_mul_f32_e32 v126, 0x3b000000, v104
	v_pk_add_f32 v[104:105], v[100:101], v[128:129] op_sel_hi:[1,0] neg_lo:[0,1] neg_hi:[0,1]
	v_pk_add_f32 v[106:107], v[102:103], v[128:129] op_sel_hi:[1,0] neg_lo:[0,1] neg_hi:[0,1]
	v_pk_mul_f32 v[130:131], v[104:105], v[104:105]
	v_pk_mul_f32 v[132:133], v[106:107], v[106:107]
	v_add_f32_e32 v125, v130, v131
	v_pk_add_f32 v[100:101], v[108:109], v[128:129] op_sel_hi:[1,0] neg_lo:[0,1] neg_hi:[0,1]
	v_add_f32_e32 v125, v132, v125
	v_pk_mul_f32 v[108:109], v[100:101], v[100:101]
	v_add_f32_e32 v125, v133, v125
	v_pk_add_f32 v[102:103], v[110:111], v[128:129] op_sel_hi:[1,0] neg_lo:[0,1] neg_hi:[0,1]
	v_add_f32_e32 v108, v108, v125
	v_pk_mul_f32 v[110:111], v[102:103], v[102:103]
	v_add_f32_e32 v108, v109, v108
	v_add_f32_e32 v108, v110, v108
	v_add_f32_e32 v108, v111, v108
	ds_bpermute_b32 v109, v112, v108
	v_pk_add_f32 v[6:7], v[6:7], v[126:127] op_sel_hi:[1,0] neg_lo:[0,1] neg_hi:[0,1]
	v_pk_add_f32 v[2:3], v[2:3], v[126:127] op_sel_hi:[1,0] neg_lo:[0,1] neg_hi:[0,1]
	v_pk_mul_f32 v[128:129], v[6:7], v[6:7]
	v_pk_mul_f32 v[130:131], v[2:3], v[2:3]
	s_waitcnt lgkmcnt(0)
	v_add_f32_e32 v108, v108, v109
	ds_bpermute_b32 v109, v113, v108
	v_pk_add_f32 v[132:133], v[8:9], v[126:127] op_sel_hi:[1,0] neg_lo:[0,1] neg_hi:[0,1]
	v_pk_add_f32 v[4:5], v[4:5], v[126:127] op_sel_hi:[1,0] neg_lo:[0,1] neg_hi:[0,1]
	v_pk_mul_f32 v[8:9], v[132:133], v[132:133]
	v_pk_mul_f32 v[126:127], v[4:5], v[4:5]
	s_waitcnt lgkmcnt(0)
	v_add_f32_e32 v108, v108, v109
	ds_bpermute_b32 v109, v114, v108
	ds_bpermute_b32 v121, v117, v119
	s_waitcnt lgkmcnt(1)
	v_add_f32_e32 v108, v108, v109
	ds_bpermute_b32 v109, v115, v108
	s_waitcnt lgkmcnt(0)
	v_add_f32_e32 v108, v108, v109
	ds_bpermute_b32 v109, v116, v108
	s_waitcnt lgkmcnt(0)
	v_add_f32_e32 v110, v108, v109
	v_add_f32_e32 v109, v128, v129
	v_add_f32_e32 v109, v130, v109
	v_add_f32_e32 v109, v131, v109
	v_add_f32_e32 v8, v8, v109
	v_add_f32_e32 v8, v9, v8
	v_add_f32_e32 v8, v126, v8
	v_add_f32_e32 v8, v127, v8
	ds_bpermute_b32 v9, v112, v8
	ds_bpermute_b32 v111, v117, v110
	v_add_u32_e32 v108, 0xffff0000, v62
	s_waitcnt lgkmcnt(1)
	v_add_f32_e32 v8, v8, v9
	ds_bpermute_b32 v9, v113, v8
	s_waitcnt lgkmcnt(0)
	v_add_f32_e32 v8, v8, v9
	ds_bpermute_b32 v9, v114, v8
	s_waitcnt lgkmcnt(0)
	v_add_f32_e32 v8, v8, v9
	ds_bpermute_b32 v9, v115, v8
	s_waitcnt lgkmcnt(0)
	v_add_f32_e32 v8, v8, v9
	ds_bpermute_b32 v9, v116, v8
	s_waitcnt lgkmcnt(0)
	v_add_f32_e32 v8, v8, v9
	ds_bpermute_b32 v9, v117, v8
	s_waitcnt lgkmcnt(0)
	v_add_f32_e32 v8, v8, v9
	v_fmamk_f32 v8, v8, 0x3b000000, v246
	v_cmp_gt_f32_e64 s[0:1], s34, v8
	v_mul_f32_e32 v9, 0x4b800000, v8
	s_nop 0
	v_cndmask_b32_e64 v8, v8, v9, s[0:1]
	v_rsq_f32_e32 v8, v8
	s_nop 0
	v_mul_f32_e32 v9, 0x45800000, v8
	v_cndmask_b32_e64 v126, v8, v9, s[0:1]
	v_pk_mul_f32 v[2:3], v[2:3], v[126:127] op_sel_hi:[1,0]
	v_pk_mul_f32 v[6:7], v[6:7], v[126:127] op_sel_hi:[1,0]
	v_pk_fma_f32 v[8:9], v[38:39], v[2:3], v[40:41]
	v_pk_mul_f32 v[2:3], v[132:133], v[126:127] op_sel_hi:[1,0]
	v_pk_mul_f32 v[4:5], v[4:5], v[126:127] op_sel_hi:[1,0]
	v_pk_fma_f32 v[6:7], v[28:29], v[6:7], v[30:31]
	v_pk_fma_f32 v[2:3], v[46:47], v[2:3], v[48:49]
	v_pk_fma_f32 v[4:5], v[54:55], v[4:5], v[56:57]
	s_mov_b32 s0, 0xffff
	v_cvt_pk_bf16_f32 v126, v6, v7
	v_cvt_pk_bf16_f32 v127, v8, v9
	v_cvt_pk_bf16_f32 v128, v2, v3
	v_cvt_pk_bf16_f32 v129, v4, v5
	v_cmp_lt_i32_e64 s[44:45], s0, v62
	global_store_dwordx4 v[86:87], v[126:129], off offset:1024
	s_and_saveexec_b64 s[0:1], s[44:45]
	s_cbranch_execz .LBB0_423
	v_mov_b32_e32 v109, v1
	v_lshlrev_b64 v[126:127], 11, v[108:109]
	v_lshl_add_u64 v[126:127], v[66:67], 0, v[126:127]
	global_store_dwordx4 v[126:127], v[6:9], off
	global_store_dwordx4 v[126:127], v[2:5], off offset:16
